# combo17 + row-pass 1/2 parameter staging de-serialised: per block all modulation/LN-affine loads issued first into dead registers, one vmcnt(0), then the LDS writes (was a load-pair -> wait -> write l
# speedup vs baseline: 1.0097x; 1.0031x over previous
; __device__ __forceinline__ int opaque_tid() { int t; asm volatile("v_mov_b32 %0, %1" : "=v"(t) : "v"((int)threadIdx.x)); return t; }
; __device__ __forceinline__ void row_pass(const Params& P, int l, int mode, LAS float* pl) {
;     ...
;     { const int t_ = opaque_tid();
;       for (int i = t_; i < 3 * DM; i += NTHREADS) { const int mvi = i >> 10, c = i & 1023;
;           if (mode != 0) pl[i] = mod[(size_t)(l * 3 + mvi) * NMOD + gidx * DM + c];
;           if (make_h) { pl[5120 + i] = mod[(size_t)(ml * 3 + mvi) * NMOD + shi * DM + c]; pl[8192 + i] = mod[(size_t)(ml * 3 + mvi) * NMOD + (shi + 1) * DM + c] + 1.0f; } }
;       if (mode != 0) for (int i = t_; i < DM; i += NTHREADS) { pl[3072 + i] = lg[i]; pl[4096 + i] = lb[i]; }
;       asm volatile("s_waitcnt lgkmcnt(0)" ::: "memory"); __syncthreads(); }
.LBB0_941:
	v_ashrrev_i32_e32 v0, 10, v4
	v_ashrrev_i32_e32 v3, 10, v5
	v_and_b32_e32 v20, 0x3ff, v4
	v_add_u32_e32 v22, s69, v0
	v_mov_b64_e32 v[12:13], s[18:19]
	v_and_b32_e32 v17, 0x3ff, v5
	v_add_u32_e32 v3, s69, v3
	v_mad_i64_i32 v[14:15], s[14:15], v22, s20, v[12:13]
	v_lshlrev_b32_e32 v0, 2, v20
	v_mad_i64_i32 v[18:19], s[14:15], v3, s20, v[12:13]
	v_lshl_add_u64 v[14:15], v[14:15], 0, v[0:1]
	v_lshlrev_b32_e32 v20, 2, v17
	v_mov_b32_e32 v21, v1
	v_lshl_add_u64 v[18:19], v[18:19], 0, v[20:21]
	global_load_dword v176, v[14:15], off
	s_nop 0
	global_load_dword v177, v[18:19], off
	v_add_u32_e32 v10, -2, v10
	s_add_i32 s3, s3, 4
	v_mov_b64_e32 v[14:15], s[16:17]
	v_mad_i64_i32 v[18:19], s[14:15], v22, s20, v[14:15]
	v_mad_i64_i32 v[22:23], s[14:15], v3, s20, v[14:15]
	v_lshl_add_u64 v[18:19], v[18:19], 0, v[0:1]
	v_lshl_add_u64 v[22:23], v[22:23], 0, v[20:21]
	global_load_dword v178, v[18:19], off
	global_load_dword v179, v[22:23], off
	v_add_co_u32_e32 v18, vcc, s21, v18
	v_addc_co_u32_e32 v19, vcc, 0, v19, vcc
	v_add_co_u32_e32 v22, vcc, s21, v22
	global_load_dword v180, v[18:19], off
	s_nop 0
	v_addc_co_u32_e32 v23, vcc, 0, v23, vcc
	global_load_dword v181, v[22:23], off
	v_add_u32_e32 v3, 0x400, v5
	v_add_u32_e32 v17, 0x400, v4
	v_ashrrev_i32_e32 v17, 10, v17
	v_ashrrev_i32_e32 v3, 10, v3
	v_add_u32_e32 v3, s69, v3
	v_add_u32_e32 v17, s69, v17
	v_add_u32_e32 v5, 0x800, v5
	v_add_u32_e32 v4, 0x800, v4
	v_mad_i64_i32 v[18:19], s[14:15], v17, s20, v[12:13]
	v_mad_i64_i32 v[12:13], s[14:15], v3, s20, v[12:13]
	v_lshl_add_u64 v[18:19], v[18:19], 0, v[0:1]
	v_lshl_add_u64 v[12:13], v[12:13], 0, v[20:21]
	global_load_dword v182, v[18:19], off
	s_nop 0
	global_load_dword v183, v[12:13], off
	v_mad_i64_i32 v[12:13], s[14:15], v17, s20, v[14:15]
	v_mad_i64_i32 v[14:15], s[14:15], v3, s20, v[14:15]
	v_lshl_add_u64 v[12:13], v[12:13], 0, v[0:1]
	v_lshl_add_u64 v[14:15], v[14:15], 0, v[20:21]
	global_load_dword v184, v[12:13], off
	global_load_dword v185, v[14:15], off
	v_add_co_u32_e32 v12, vcc, s21, v12
	v_addc_co_u32_e32 v13, vcc, 0, v13, vcc
	v_add_co_u32_e32 v14, vcc, s21, v14
	global_load_dword v186, v[12:13], off
	s_nop 0
	v_addc_co_u32_e32 v15, vcc, 0, v15, vcc
	global_load_dword v187, v[14:15], off
	v_cmp_eq_u32_e32 vcc, 0, v10
	s_or_b64 s[12:13], vcc, s[12:13]
	v_mov_b32_e32 v0, s3
	s_waitcnt vmcnt(0)
	ds_write2st64_b32 v11, v176, v177 offset1:8
	ds_write2st64_b32 v11, v178, v179 offset0:80 offset1:88
	v_pk_add_f32 v[180:181], v[180:181], 1.0 op_sel_hi:[1,0]
	ds_write2st64_b32 v11, v180, v181 offset0:128 offset1:136
	ds_write2st64_b32 v11, v182, v183 offset0:16 offset1:24
	ds_write2st64_b32 v11, v184, v185 offset0:96 offset1:104
	v_pk_add_f32 v[186:187], v[186:187], 1.0 op_sel_hi:[1,0]
	ds_write2st64_b32 v11, v186, v187 offset0:144 offset1:152
	v_add_u32_e32 v11, 0x2000, v11
	s_andn2_b64 exec, exec, s[12:13]
	s_cbranch_execnz .LBB0_941
	s_or_b64 exec, exec, s[12:13]
	v_lshlrev_b32_e32 v10, 9, v0
.LBB0_943:
	s_or_b64 exec, exec, s[4:5]
	v_and_b32_e32 v0, 2, v9
	v_cmp_eq_u32_e32 vcc, 0, v0
	s_and_saveexec_b64 s[4:5], vcc
	s_cbranch_execz .LBB0_945
	v_readlane_b32 s12, v254, 14
	v_ashrrev_i32_e32 v0, 10, v4
	v_ashrrev_i32_e32 v3, 10, v5
	v_readlane_b32 s13, v254, 15
	v_and_b32_e32 v9, 0x3ff, v5
	v_and_b32_e32 v11, 0x3ff, v4
	v_add_u32_e32 v3, s69, v3
	v_add_u32_e32 v17, s69, v0
	v_mov_b64_e32 v[4:5], s[12:13]
	s_movk_i32 s3, 0x6000
	v_mad_i64_i32 v[12:13], s[12:13], v17, s3, v[4:5]
	v_mad_i64_i32 v[4:5], s[12:13], v3, s3, v[4:5]
	v_lshlrev_b32_e32 v0, 2, v11
	v_lshlrev_b32_e32 v14, 2, v9
	v_mov_b32_e32 v15, v1
	v_lshl_add_u64 v[12:13], v[12:13], 0, v[0:1]
	v_lshl_add_u64 v[4:5], v[4:5], 0, v[14:15]
	global_load_dword v176, v[12:13], off
	s_nop 0
	global_load_dword v177, v[4:5], off
	v_readlane_b32 s12, v254, 12
	v_lshl_add_u32 v10, v10, 2, v8
	v_readlane_b32 s13, v254, 13
	v_mov_b64_e32 v[4:5], s[12:13]
	v_mad_i64_i32 v[8:9], s[12:13], v17, s3, v[4:5]
	v_mad_i64_i32 v[4:5], s[12:13], v3, s3, v[4:5]
	v_lshl_add_u64 v[8:9], v[8:9], 0, v[0:1]
	s_movk_i32 s3, 0x1000
	v_lshl_add_u64 v[4:5], v[4:5], 0, v[14:15]
	global_load_dword v178, v[8:9], off
	global_load_dword v179, v[4:5], off
	v_add_co_u32_e32 v8, vcc, s3, v8
	v_addc_co_u32_e32 v9, vcc, 0, v9, vcc
	v_add_co_u32_e32 v4, vcc, 0x1000, v4
	global_load_dword v180, v[8:9], off
	s_nop 0
	v_addc_co_u32_e32 v5, vcc, 0, v5, vcc
	global_load_dword v181, v[4:5], off
	s_waitcnt vmcnt(0)
	ds_write2st64_b32 v10, v176, v177 offset1:8
	ds_write2st64_b32 v10, v178, v179 offset0:80 offset1:88
	v_pk_add_f32 v[182:183], v[180:181], 1.0 op_sel_hi:[1,0]
	ds_write2st64_b32 v10, v182, v183 offset0:128 offset1:136

; __device__ __forceinline__ void row_pass(const Params& P, int l, int mode, LAS float* pl) {
;     ...
;       for (int i = t_; i < 3 * DM; i += NTHREADS) { const int mvi = i >> 10, c = i & 1023;
;           if (mode != 0) pl[i] = mod[(size_t)(l * 3 + mvi) * NMOD + gidx * DM + c];
;           if (make_h) { pl[5120 + i] = mod[(size_t)(ml * 3 + mvi) * NMOD + shi * DM + c]; pl[8192 + i] = mod[(size_t)(ml * 3 + mvi) * NMOD + (shi + 1) * DM + c] + 1.0f; } }
.LBB0_949:
	v_ashrrev_i32_e32 v0, 10, v3
	v_and_b32_e32 v5, 0x3ff, v3
	v_add_u32_e32 v7, s69, v0
	v_mov_b64_e32 v[8:9], s[10:11]
	v_mad_i64_i32 v[8:9], s[4:5], v7, s3, v[8:9]
	v_lshlrev_b32_e32 v0, 2, v5
	v_lshl_add_u64 v[8:9], v[8:9], 0, v[0:1]
	global_load_dword v176, v[8:9], off
	v_mov_b64_e32 v[8:9], s[8:9]
	v_mad_i64_i32 v[8:9], s[4:5], v7, s3, v[8:9]
	v_lshl_add_u64 v[8:9], v[8:9], 0, v[0:1]
	global_load_dword v177, v[8:9], off
	v_add_co_u32_e32 v8, vcc, 0x1000, v8
	v_addc_co_u32_e32 v9, vcc, 0, v9, vcc
	global_load_dword v178, v[8:9], off
	v_cmp_lt_i32_e32 vcc, s12, v3
	s_or_b64 s[0:1], vcc, s[0:1]
	s_waitcnt vmcnt(0)
	ds_write2st64_b32 v4, v176, v177 offset1:80
	v_add_f32_e32 v178, 1.0, v178
	ds_write_b32 v4, v178 offset:32768
	v_add_u32_e32 v0, 0x200, v3
	v_add_u32_e32 v4, 0x800, v4
	v_mov_b32_e32 v3, v0
	s_andn2_b64 exec, exec, s[0:1]
	s_cbranch_execnz .LBB0_949

; __device__ __forceinline__ void row_pass(const Params& P, int l, int mode, LAS float* pl) {
;     ...
;       if (mode != 0) for (int i = t_; i < DM; i += NTHREADS) { pl[3072 + i] = lg[i]; pl[4096 + i] = lb[i]; }
.LBB0_955:
	v_ashrrev_i32_e32 v15, 31, v4
	v_mov_b32_e32 v14, v4
	v_ashrrev_i32_e32 v13, 31, v5
	v_mov_b32_e32 v12, v5
	v_lshl_add_u64 v[14:15], v[14:15], 2, s[4:5]
	v_lshl_add_u64 v[12:13], v[12:13], 2, s[4:5]
	global_load_dword v176, v[14:15], off
	global_load_dword v177, v[12:13], off
	v_add_u32_e32 v12, 0x400, v4
	v_add_u32_e32 v14, 0x400, v5
	v_ashrrev_i32_e32 v13, 31, v12
	v_ashrrev_i32_e32 v15, 31, v14
	v_lshl_add_u64 v[12:13], v[12:13], 2, s[4:5]
	v_lshl_add_u64 v[14:15], v[14:15], 2, s[4:5]
	v_add_u32_e32 v10, -4, v10
	s_add_i32 s3, s3, 8
	v_cmp_eq_u32_e32 vcc, 0, v10
	s_or_b64 s[16:17], vcc, s[16:17]
	global_load_dword v178, v[12:13], off
	global_load_dword v179, v[14:15], off
	v_add_u32_e32 v12, 0x800, v4
	v_add_u32_e32 v14, 0x800, v5
	v_ashrrev_i32_e32 v13, 31, v12
	v_ashrrev_i32_e32 v15, 31, v14
	v_lshlrev_b64 v[12:13], 2, v[12:13]
	v_lshl_add_u64 v[18:19], s[4:5], 0, v[12:13]
	v_lshlrev_b64 v[14:15], 2, v[14:15]
	v_lshl_add_u64 v[20:21], s[4:5], 0, v[14:15]
	v_lshl_add_u64 v[12:13], s[12:13], 0, v[12:13]
	v_lshl_add_u64 v[14:15], s[12:13], 0, v[14:15]
	global_load_dword v180, v[18:19], off
	global_load_dword v181, v[20:21], off
	global_load_dword v182, v[12:13], off
	global_load_dword v183, v[14:15], off
	v_add_u32_e32 v12, 0xc00, v4
	v_add_u32_e32 v14, 0xc00, v5
	v_ashrrev_i32_e32 v13, 31, v12
	v_ashrrev_i32_e32 v15, 31, v14
	v_lshlrev_b64 v[12:13], 2, v[12:13]
	v_lshl_add_u64 v[18:19], s[4:5], 0, v[12:13]
	v_lshlrev_b64 v[14:15], 2, v[14:15]
	v_lshl_add_u64 v[20:21], s[4:5], 0, v[14:15]
	v_lshl_add_u64 v[12:13], s[12:13], 0, v[12:13]
	v_lshl_add_u64 v[14:15], s[12:13], 0, v[14:15]
	v_add_u32_e32 v5, 0x1000, v5
	v_add_u32_e32 v4, 0x1000, v4
	global_load_dword v184, v[18:19], off
	global_load_dword v185, v[20:21], off
	global_load_dword v186, v[12:13], off
	global_load_dword v187, v[14:15], off
	v_add_u32_e32 v12, 0x4000, v9
	s_waitcnt vmcnt(0)
	ds_write2st64_b32 v9, v176, v177 offset1:8
	ds_write2st64_b32 v9, v178, v179 offset0:16 offset1:24
	ds_write2st64_b32 v9, v180, v181 offset0:32 offset1:40
	ds_write_b32 v9, v182 offset:12288
	ds_write2st64_b32 v9, v184, v183 offset0:48 offset1:56
	ds_write2st64_b32 v9, v185, v186 offset0:56 offset1:64
	ds_write_b32 v9, v187 offset:18432
	v_mov_b32_e32 v11, s3
	v_mov_b32_e32 v9, v12
	s_andn2_b64 exec, exec, s[16:17]
	s_cbranch_execnz .LBB0_955
	s_or_b64 exec, exec, s[16:17]

; __device__ __forceinline__ void row_pass(const Params& P, int l, int mode, LAS float* pl) {
;     ...
;       if (mode != 0) for (int i = t_; i < DM; i += NTHREADS) { pl[3072 + i] = lg[i]; pl[4096 + i] = lb[i]; }
.LBB0_959:
	v_ashrrev_i32_e32 v11, 31, v4
	v_mov_b32_e32 v10, v4
	v_ashrrev_i32_e32 v9, 31, v5
	v_mov_b32_e32 v8, v5
	v_lshlrev_b64 v[10:11], 2, v[10:11]
	v_lshl_add_u64 v[12:13], s[4:5], 0, v[10:11]
	v_lshlrev_b64 v[8:9], 2, v[8:9]
	v_lshl_add_u64 v[14:15], s[4:5], 0, v[8:9]
	global_load_dword v176, v[12:13], off
	s_nop 0
	global_load_dword v177, v[14:15], off
	v_lshl_add_u64 v[10:11], s[12:13], 0, v[10:11]
	v_lshl_add_u64 v[8:9], s[12:13], 0, v[8:9]
	v_add_u32_e32 v3, -1, v3
	v_cmp_eq_u32_e32 vcc, 0, v3
	v_add_u32_e32 v5, 0x400, v5
	v_add_u32_e32 v4, 0x400, v4
	s_or_b64 s[16:17], vcc, s[16:17]
	global_load_dword v178, v[10:11], off
	s_nop 0
	global_load_dword v179, v[8:9], off
	v_add_u32_e32 v9, 0x1000, v7
	s_waitcnt vmcnt(0)
	ds_write2st64_b32 v7, v176, v177 offset1:8
	ds_write2st64_b32 v7, v178, v179 offset0:16 offset1:24
	v_mov_b32_e32 v7, v9
	s_andn2_b64 exec, exec, s[16:17]
	s_cbranch_execnz .LBB0_959

; __device__ __forceinline__ void row_pass(const Params& P, int l, int mode, LAS float* pl) {
;     ...
;       for (int i = t_; i < 3 * DM; i += NTHREADS) { const int mvi = i >> 10, c = i & 1023;
;           if (mode != 0) pl[i] = mod[(size_t)(l * 3 + mvi) * NMOD + gidx * DM + c];
;           if (make_h) { pl[5120 + i] = mod[(size_t)(ml * 3 + mvi) * NMOD + shi * DM + c]; pl[8192 + i] = mod[(size_t)(ml * 3 + mvi) * NMOD + (shi + 1) * DM + c] + 1.0f; } }
.LBB0_1243:
	v_readlane_b32 s8, v254, 18
	v_ashrrev_i32_e32 v0, 10, v4
	v_readlane_b32 s9, v254, 19
	v_and_b32_e32 v7, 0x3ff, v4
	v_add_u32_e32 v5, s69, v0
	v_mov_b64_e32 v[8:9], s[8:9]
	v_mad_i64_i32 v[8:9], s[8:9], v5, s79, v[8:9]
	v_lshlrev_b32_e32 v0, 2, v7
	v_lshl_add_u64 v[8:9], v[8:9], 0, v[0:1]
	global_load_dword v110, v[8:9], off
	s_andn2_b64 vcc, exec, s[36:37]
	s_cbranch_vccnz .Lstg2_a
	v_readlane_b32 s8, v253, 55
	v_readlane_b32 s9, v253, 56
	v_add_u32_e32 v5, 3, v5
	s_nop 0
	v_mov_b64_e32 v[8:9], s[8:9]
	v_mad_i64_i32 v[8:9], s[8:9], v5, s79, v[8:9]
	v_lshl_add_u64 v[8:9], v[8:9], 0, v[0:1]
	v_add_co_u32_e32 v10, vcc, 0x1000, v8
	s_nop 1
	v_addc_co_u32_e32 v11, vcc, 0, v9, vcc
	global_load_dword v111, v[10:11], off
	global_load_dword v112, v[8:9], off
.Lstg2_a:
	s_waitcnt vmcnt(0)
	ds_write_b32 v3, v110
	s_andn2_b64 vcc, exec, s[36:37]
	s_cbranch_vccnz .LBB0_1242
	v_add_f32_e32 v111, 1.0, v111
	ds_write2st64_b32 v3, v112, v111 offset0:80 offset1:128
	s_branch .LBB0_1242

; __device__ __forceinline__ void row_pass(const Params& P, int l, int mode, LAS float* pl) {
;     ...
;       if (mode != 0) for (int i = t_; i < DM; i += NTHREADS) { pl[3072 + i] = lg[i]; pl[4096 + i] = lb[i]; }
.LBB0_1250:
	v_ashrrev_i32_e32 v15, 31, v4
	v_mov_b32_e32 v14, v4
	v_ashrrev_i32_e32 v13, 31, v5
	v_mov_b32_e32 v12, v5
	v_lshl_add_u64 v[14:15], v[14:15], 2, s[6:7]
	v_lshl_add_u64 v[12:13], v[12:13], 2, s[6:7]
	global_load_dword v98, v[14:15], off
	global_load_dword v99, v[12:13], off
	v_add_u32_e32 v12, 0x400, v4
	v_add_u32_e32 v14, 0x400, v5
	v_ashrrev_i32_e32 v13, 31, v12
	v_ashrrev_i32_e32 v15, 31, v14
	v_lshl_add_u64 v[12:13], v[12:13], 2, s[6:7]
	v_lshl_add_u64 v[14:15], v[14:15], 2, s[6:7]
	v_add_u32_e32 v9, -4, v9
	s_add_i32 s3, s3, 8
	v_cmp_eq_u32_e32 vcc, 0, v9
	s_or_b64 s[18:19], vcc, s[18:19]
	global_load_dword v100, v[12:13], off
	global_load_dword v101, v[14:15], off
	v_add_u32_e32 v12, 0x800, v4
	v_add_u32_e32 v14, 0x800, v5
	v_ashrrev_i32_e32 v13, 31, v12
	v_ashrrev_i32_e32 v15, 31, v14
	v_lshlrev_b64 v[12:13], 2, v[12:13]
	v_lshl_add_u64 v[18:19], s[6:7], 0, v[12:13]
	v_lshlrev_b64 v[14:15], 2, v[14:15]
	v_lshl_add_u64 v[20:21], s[6:7], 0, v[14:15]
	v_lshl_add_u64 v[12:13], s[14:15], 0, v[12:13]
	v_lshl_add_u64 v[14:15], s[14:15], 0, v[14:15]
	global_load_dword v102, v[18:19], off
	global_load_dword v103, v[20:21], off
	global_load_dword v104, v[12:13], off
	global_load_dword v105, v[14:15], off
	v_add_u32_e32 v12, 0xc00, v4
	v_add_u32_e32 v14, 0xc00, v5
	v_ashrrev_i32_e32 v13, 31, v12
	v_ashrrev_i32_e32 v15, 31, v14
	v_lshlrev_b64 v[12:13], 2, v[12:13]
	v_lshl_add_u64 v[18:19], s[6:7], 0, v[12:13]
	v_lshlrev_b64 v[14:15], 2, v[14:15]
	v_lshl_add_u64 v[20:21], s[6:7], 0, v[14:15]
	v_lshl_add_u64 v[12:13], s[14:15], 0, v[12:13]
	v_lshl_add_u64 v[14:15], s[14:15], 0, v[14:15]
	v_add_u32_e32 v5, 0x1000, v5
	v_add_u32_e32 v4, 0x1000, v4
	global_load_dword v106, v[18:19], off
	global_load_dword v107, v[20:21], off
	global_load_dword v108, v[12:13], off
	global_load_dword v109, v[14:15], off
	v_add_u32_e32 v12, 0x4000, v10
	s_waitcnt vmcnt(0)
	ds_write2st64_b32 v10, v98, v99 offset1:8
	ds_write2st64_b32 v10, v100, v101 offset0:16 offset1:24
	ds_write2st64_b32 v10, v102, v103 offset0:32 offset1:40
	ds_write_b32 v10, v104 offset:12288
	ds_write2st64_b32 v10, v106, v105 offset0:48 offset1:56
	ds_write2st64_b32 v10, v107, v108 offset0:56 offset1:64
	ds_write_b32 v10, v109 offset:18432
	v_mov_b32_e32 v11, s3
	v_mov_b32_e32 v10, v12
	s_andn2_b64 exec, exec, s[18:19]
	s_cbranch_execnz .LBB0_1250
	s_or_b64 exec, exec, s[18:19]

; __device__ __forceinline__ void row_pass(const Params& P, int l, int mode, LAS float* pl) {
;     ...
;       if (mode != 0) for (int i = t_; i < DM; i += NTHREADS) { pl[3072 + i] = lg[i]; pl[4096 + i] = lb[i]; }
.LBB0_1254:
	v_ashrrev_i32_e32 v11, 31, v4
	v_mov_b32_e32 v10, v4
	v_ashrrev_i32_e32 v9, 31, v5
	v_mov_b32_e32 v8, v5
	v_lshlrev_b64 v[10:11], 2, v[10:11]
	v_lshl_add_u64 v[12:13], s[6:7], 0, v[10:11]
	v_lshlrev_b64 v[8:9], 2, v[8:9]
	v_lshl_add_u64 v[14:15], s[6:7], 0, v[8:9]
	global_load_dword v98, v[12:13], off
	s_nop 0
	global_load_dword v99, v[14:15], off
	v_lshl_add_u64 v[10:11], s[14:15], 0, v[10:11]
	v_lshl_add_u64 v[8:9], s[14:15], 0, v[8:9]
	v_add_u32_e32 v3, -1, v3
	v_cmp_eq_u32_e32 vcc, 0, v3
	v_add_u32_e32 v5, 0x400, v5
	v_add_u32_e32 v4, 0x400, v4
	s_or_b64 s[18:19], vcc, s[18:19]
	global_load_dword v100, v[10:11], off
	s_nop 0
	global_load_dword v101, v[8:9], off
	v_add_u32_e32 v9, 0x1000, v7
	s_waitcnt vmcnt(0)
	ds_write2st64_b32 v7, v98, v99 offset1:8
	ds_write2st64_b32 v7, v100, v101 offset0:16 offset1:24
	v_mov_b32_e32 v7, v9
	s_andn2_b64 exec, exec, s[18:19]
	s_cbranch_execnz .LBB0_1254
